# grid barrier: all workgroups poll the top generation word directly (one less release hop), XGEN add removed
# speedup vs baseline: 1.0059x; 1.0023x over previous
; __device__ __forceinline__ unsigned xb_ld(unsigned* p)              { return __hip_atomic_load(p, __ATOMIC_RELAXED, __HIP_MEMORY_SCOPE_AGENT); }
; __device__ __forceinline__ unsigned xb_add(unsigned* p, unsigned v) { return __hip_atomic_fetch_add(p, v, __ATOMIC_RELAXED, __HIP_MEMORY_SCOPE_AGENT); }
; #define XB_SPIN(cond, bar) do { unsigned _sp = 0; while (cond) { __builtin_amdgcn_s_sleep(1); \
;     if ((++_sp & 255u) == 0u) { if (xb_ld(&(bar)[XB_TMO])) break; if (_sp > XB_SPIN_CAP) { atomicAdd(&(bar)[XB_TMO], 1u); break; } } } } while (0)
; __device__ __forceinline__ void xcd_barrier(const XcdBarrier& b) {
;     ...
;         const unsigned old = xb_add(&bar[XB_XSUB(b.x)], 1u);
;         const unsigned gen = old / nloc;
;         if (old + 1u == (gen + 1u) * nloc) {
;             __builtin_amdgcn_fence(__ATOMIC_RELEASE, "agent");
;             asm volatile("s_waitcnt vmcnt(0)" ::: "memory");
;             const unsigned og = xb_add(&bar[XB_TOP], 1u);
;             const unsigned tg = og / nx;
;             if (og + 1u == (tg + 1u) * nx) xb_add(&bar[XB_TOPGEN], 1u);
;             else XB_SPIN(xb_ld(&bar[XB_TOPGEN]) == tg, bar);
;             __builtin_amdgcn_fence(__ATOMIC_ACQUIRE, "agent");
;             xb_add(&bar[XB_XGEN(b.x)], 1u);
;             asm volatile("s_waitcnt vmcnt(0)" ::: "memory");
;         } else {
;             XB_SPIN(xb_ld(&bar[XB_XGEN(b.x)]) == gen, bar);
.LBB0_102:
	s_or_b64 exec, exec, s[2:3]
	v_cvt_f32_u32_e32 v4, v2
	s_waitcnt vmcnt(0)
	v_readfirstlane_b32 s2, v3
	v_sub_u32_e32 v3, 0, v2
	v_rcp_iflag_f32_e32 v4, v4
	v_add_u32_e32 v5, s2, v1
	v_mul_f32_e32 v4, 0x4f7ffffe, v4
	v_cvt_u32_f32_e32 v4, v4
	v_mul_lo_u32 v1, v3, v4
	v_mul_hi_u32 v1, v4, v1
	v_add_u32_e32 v1, v4, v1
	v_mul_hi_u32 v1, v5, v1
	v_mul_lo_u32 v3, v1, v2
	v_sub_u32_e32 v3, v5, v3
	v_add_u32_e32 v4, 1, v1
	v_cmp_ge_u32_e32 vcc, v3, v2
	s_nop 1
	v_cndmask_b32_e32 v1, v1, v4, vcc
	v_sub_u32_e32 v4, v3, v2
	v_cndmask_b32_e32 v3, v3, v4, vcc
	v_add_u32_e32 v4, 1, v1
	v_cmp_ge_u32_e32 vcc, v3, v2
	v_add_u32_e32 v3, 1, v5
	s_nop 0
	v_cndmask_b32_e32 v1, v1, v4, vcc
	v_mul_lo_u32 v4, v2, v1
	v_add_u32_e32 v2, v4, v2
	v_cmp_ne_u32_e32 vcc, v3, v2
	s_and_saveexec_b64 s[2:3], vcc
	s_xor_b64 s[2:3], exec, s[2:3]
	s_cbranch_execz .LBB0_116
	v_readlane_b32 s10, v254, 47
	s_waitcnt lgkmcnt(0)
	v_mov_b32_e32 v0, 0
	v_readlane_b32 s11, v254, 48
	s_nop 4
	global_load_dword v2, v0, s[10:11] sc1
	s_waitcnt vmcnt(0)
	v_cmp_eq_u32_e32 vcc, v2, v1
	s_and_saveexec_b64 s[12:13], vcc
	s_cbranch_execz .LBB0_115
	s_mov_b32 s10, 1
	s_mov_b64 s[14:15], 0
	s_branch .LBB0_106

; __device__ __forceinline__ unsigned xb_ld(unsigned* p)              { return __hip_atomic_load(p, __ATOMIC_RELAXED, __HIP_MEMORY_SCOPE_AGENT); }
; #define XB_SPIN(cond, bar) do { unsigned _sp = 0; while (cond) { __builtin_amdgcn_s_sleep(1); \
;     if ((++_sp & 255u) == 0u) { if (xb_ld(&(bar)[XB_TMO])) break; if (_sp > XB_SPIN_CAP) { atomicAdd(&(bar)[XB_TMO], 1u); break; } } } } while (0)
; __device__ __forceinline__ void xcd_barrier(const XcdBarrier& b) {
;     ...
;             XB_SPIN(xb_ld(&bar[XB_XGEN(b.x)]) == gen, bar);
.LBB0_108:
	v_readlane_b32 s18, v254, 47
	v_readlane_b32 s19, v254, 48
	s_add_i32 s10, s10, 1
	s_mov_b64 s[20:21], -1
	s_nop 2
	global_load_dword v2, v0, s[18:19] sc1
	s_waitcnt vmcnt(0)
	v_cmp_ne_u32_e32 vcc, v2, v1
	s_orn2_b64 s[18:19], vcc, exec
	s_branch .LBB0_105

; __device__ __forceinline__ unsigned xb_ld(unsigned* p)              { return __hip_atomic_load(p, __ATOMIC_RELAXED, __HIP_MEMORY_SCOPE_AGENT); }
; __device__ __forceinline__ unsigned xb_add(unsigned* p, unsigned v) { return __hip_atomic_fetch_add(p, v, __ATOMIC_RELAXED, __HIP_MEMORY_SCOPE_AGENT); }
; #define XB_SPIN(cond, bar) do { unsigned _sp = 0; while (cond) { __builtin_amdgcn_s_sleep(1); \
;     if ((++_sp & 255u) == 0u) { if (xb_ld(&(bar)[XB_TMO])) break; if (_sp > XB_SPIN_CAP) { atomicAdd(&(bar)[XB_TMO], 1u); break; } } } } while (0)
; __device__ __forceinline__ void xcd_barrier(const XcdBarrier& b) {
;     ...
;             else XB_SPIN(xb_ld(&bar[XB_TOPGEN]) == tg, bar);
;             __builtin_amdgcn_fence(__ATOMIC_ACQUIRE, "agent");
;             xb_add(&bar[XB_XGEN(b.x)], 1u);
;             asm volatile("s_waitcnt vmcnt(0)" ::: "memory");
.LBB0_133:
	s_or_b64 exec, exec, s[2:3]
	s_mov_b64 s[2:3], exec
	v_mbcnt_lo_u32_b32 v0, s2, 0
	v_mbcnt_hi_u32_b32 v0, s3, v0
	v_cmp_eq_u32_e32 vcc, 0, v0
	s_waitcnt vmcnt(0)
	buffer_inv sc1
	s_and_saveexec_b64 s[12:13], vcc
	s_cbranch_execz .LBB0_135
	s_bcnt1_i32_b64 s2, s[2:3]
	v_mov_b32_e32 v1, s2
	v_readlane_b32 s2, v254, 43
	v_mov_b32_e32 v0, 0
	v_readlane_b32 s3, v254, 44
	s_nop 4
	s_nop 0

; __device__ __forceinline__ unsigned xb_ld(unsigned* p)              { return __hip_atomic_load(p, __ATOMIC_RELAXED, __HIP_MEMORY_SCOPE_AGENT); }
; __device__ __forceinline__ unsigned xb_add(unsigned* p, unsigned v) { return __hip_atomic_fetch_add(p, v, __ATOMIC_RELAXED, __HIP_MEMORY_SCOPE_AGENT); }
; #define XB_SPIN(cond, bar) do { unsigned _sp = 0; while (cond) { __builtin_amdgcn_s_sleep(1); \
;     if ((++_sp & 255u) == 0u) { if (xb_ld(&(bar)[XB_TMO])) break; if (_sp > XB_SPIN_CAP) { atomicAdd(&(bar)[XB_TMO], 1u); break; } } } } while (0)
; __device__ __forceinline__ void xcd_barrier(const XcdBarrier& b) {
;     ...
;         const unsigned old = xb_add(&bar[XB_XSUB(b.x)], 1u);
;         const unsigned gen = old / nloc;
;         if (old + 1u == (gen + 1u) * nloc) {
;             __builtin_amdgcn_fence(__ATOMIC_RELEASE, "agent");
;             asm volatile("s_waitcnt vmcnt(0)" ::: "memory");
;             const unsigned og = xb_add(&bar[XB_TOP], 1u);
;             const unsigned tg = og / nx;
;             if (og + 1u == (tg + 1u) * nx) xb_add(&bar[XB_TOPGEN], 1u);
;             else XB_SPIN(xb_ld(&bar[XB_TOPGEN]) == tg, bar);
;             __builtin_amdgcn_fence(__ATOMIC_ACQUIRE, "agent");
;             xb_add(&bar[XB_XGEN(b.x)], 1u);
;             asm volatile("s_waitcnt vmcnt(0)" ::: "memory");
;         } else {
;             XB_SPIN(xb_ld(&bar[XB_XGEN(b.x)]) == gen, bar);
.LBB0_471:
	s_or_b64 exec, exec, s[2:3]
	v_cvt_f32_u32_e32 v5, v3
	s_waitcnt vmcnt(0)
	v_readfirstlane_b32 s2, v4
	v_sub_u32_e32 v4, 0, v3
	v_rcp_iflag_f32_e32 v5, v5
	v_add_u32_e32 v6, s2, v0
	v_mul_f32_e32 v5, 0x4f7ffffe, v5
	v_cvt_u32_f32_e32 v5, v5
	v_mul_lo_u32 v0, v4, v5
	v_mul_hi_u32 v0, v5, v0
	v_add_u32_e32 v0, v5, v0
	v_mul_hi_u32 v0, v6, v0
	v_mul_lo_u32 v4, v0, v3
	v_sub_u32_e32 v4, v6, v4
	v_add_u32_e32 v5, 1, v0
	v_cmp_ge_u32_e32 vcc, v4, v3
	s_nop 1
	v_cndmask_b32_e32 v0, v0, v5, vcc
	v_sub_u32_e32 v5, v4, v3
	v_cndmask_b32_e32 v4, v4, v5, vcc
	v_add_u32_e32 v5, 1, v0
	v_cmp_ge_u32_e32 vcc, v4, v3
	v_add_u32_e32 v4, 1, v6
	s_nop 0
	v_cndmask_b32_e32 v0, v0, v5, vcc
	v_mul_lo_u32 v5, v3, v0
	v_add_u32_e32 v3, v5, v3
	v_cmp_ne_u32_e32 vcc, v4, v3
	s_and_saveexec_b64 s[2:3], vcc
	s_xor_b64 s[2:3], exec, s[2:3]
	s_cbranch_execz .LBB0_485
	v_readlane_b32 s12, v254, 47
	v_readlane_b32 s13, v254, 48
	s_waitcnt lgkmcnt(0)
	s_nop 3
	global_load_dword v2, v1, s[12:13] sc1
	s_waitcnt vmcnt(0)
	v_cmp_eq_u32_e32 vcc, v2, v0
	s_and_saveexec_b64 s[12:13], vcc
	s_cbranch_execz .LBB0_484
	s_mov_b32 s14, 1
	s_mov_b64 s[20:21], 0
	s_branch .LBB0_475

; __device__ __forceinline__ unsigned xb_ld(unsigned* p)              { return __hip_atomic_load(p, __ATOMIC_RELAXED, __HIP_MEMORY_SCOPE_AGENT); }
; __device__ __forceinline__ unsigned xb_add(unsigned* p, unsigned v) { return __hip_atomic_fetch_add(p, v, __ATOMIC_RELAXED, __HIP_MEMORY_SCOPE_AGENT); }
; #define XB_SPIN(cond, bar) do { unsigned _sp = 0; while (cond) { __builtin_amdgcn_s_sleep(1); \
;     if ((++_sp & 255u) == 0u) { if (xb_ld(&(bar)[XB_TMO])) break; if (_sp > XB_SPIN_CAP) { atomicAdd(&(bar)[XB_TMO], 1u); break; } } } } while (0)
; __device__ __forceinline__ void xcd_barrier(const XcdBarrier& b) {
;     ...
;             else XB_SPIN(xb_ld(&bar[XB_TOPGEN]) == tg, bar);
;             __builtin_amdgcn_fence(__ATOMIC_ACQUIRE, "agent");
;             xb_add(&bar[XB_XGEN(b.x)], 1u);
;             asm volatile("s_waitcnt vmcnt(0)" ::: "memory");
.LBB0_502:
	s_or_b64 exec, exec, s[2:3]
	s_mov_b64 s[2:3], exec
	v_mbcnt_lo_u32_b32 v0, s2, 0
	v_mbcnt_hi_u32_b32 v0, s3, v0
	v_cmp_eq_u32_e32 vcc, 0, v0
	s_waitcnt vmcnt(0)
	buffer_inv sc1
	s_and_saveexec_b64 s[12:13], vcc
	s_cbranch_execz .LBB0_504
	s_bcnt1_i32_b64 s2, s[2:3]
	v_mov_b32_e32 v0, s2
	v_readlane_b32 s2, v254, 43
	v_readlane_b32 s3, v254, 44
	s_nop 4
	s_nop 0

; __device__ __forceinline__ unsigned xb_add(unsigned* p, unsigned v) { return __hip_atomic_fetch_add(p, v, __ATOMIC_RELAXED, __HIP_MEMORY_SCOPE_AGENT); }
; __device__ __forceinline__ void xcd_barrier(const XcdBarrier& b) {
;     ...
;             xb_add(&bar[XB_XGEN(b.x)], 1u);
;             asm volatile("s_waitcnt vmcnt(0)" ::: "memory");
.LBB0_1495:
	s_bcnt1_i32_b64 s2, s[2:3]
	v_mov_b32_e32 v0, s2
	v_readlane_b32 s2, v254, 43
	v_readlane_b32 s3, v254, 44
	s_nop 4
	s_nop 0
	s_getpc_b64 s[98:99]
